# same row-max permlane exchange and zero-add fold applied to the lat-B attention instantiation
# speedup vs baseline: 1.0162x; 1.0061x over previous
.LBB0_203:
	v_sub_f32_e32 v4, v96, v1
	v_exp_f32_e32 v9, v4
	v_sub_f32_e32 v5, v97, v1
	v_exp_f32_e32 v10, v5
	v_sub_f32_e32 v5, v98, v1
	v_exp_f32_e32 v11, v5
	v_sub_f32_e32 v5, v99, v1
	v_exp_f32_e32 v13, v5
	v_sub_f32_e32 v5, v100, v1
	v_exp_f32_e32 v14, v5
	v_sub_f32_e32 v5, v101, v1
	v_add_f32_e32 v4, v10, v9
	v_exp_f32_e32 v15, v5
	v_sub_f32_e32 v5, v102, v1
	v_add_f32_e32 v4, v11, v4
	v_exp_f32_e32 v96, v5
	v_sub_f32_e32 v5, v103, v1
	v_add_f32_e32 v4, v13, v4
	v_exp_f32_e32 v97, v5
	v_sub_f32_e32 v5, v104, v1
	v_add_f32_e32 v4, v14, v4
	v_exp_f32_e32 v5, v5
	v_sub_f32_e32 v6, v105, v1
	v_add_f32_e32 v4, v15, v4
	v_exp_f32_e32 v6, v6
	v_sub_f32_e32 v7, v106, v1
	v_add_f32_e32 v4, v96, v4
	v_exp_f32_e32 v7, v7
	v_sub_f32_e32 v12, v107, v1
	v_add_f32_e32 v4, v97, v4
	v_exp_f32_e32 v12, v12
	v_sub_f32_e32 v98, v108, v1
	v_add_f32_e32 v4, v5, v4
	v_exp_f32_e32 v98, v98
	v_sub_f32_e32 v99, v109, v1
	v_add_f32_e32 v4, v6, v4
	v_exp_f32_e32 v99, v99
	v_sub_f32_e32 v100, v110, v1
	v_add_f32_e32 v4, v7, v4
	v_exp_f32_e32 v100, v100
	v_sub_f32_e32 v101, v111, v1
	v_add_f32_e32 v4, v12, v4
	v_exp_f32_e32 v101, v101
	v_add_f32_e32 v4, v98, v4
	v_add_f32_e32 v4, v99, v4
	v_add_f32_e32 v4, v100, v4
	v_add_f32_e32 v4, v101, v4
	v_add_f32_e32 v3, v3, v4
	v_cvt_pk_bf16_f32 v4, v5, v6
	v_cvt_pk_bf16_f32 v5, v7, v12
	v_cvt_pk_bf16_f32 v12, v9, v10
	v_sub_f32_e32 v9, v80, v205
	v_cvt_pk_bf16_f32 v13, v11, v13
	v_exp_f32_e32 v9, v9
	v_sub_f32_e32 v11, v81, v205
	v_exp_f32_e32 v11, v11
	v_sub_f32_e32 v80, v82, v205
	v_exp_f32_e32 v81, v80
	v_sub_f32_e32 v80, v83, v205
	v_exp_f32_e32 v82, v80
	v_sub_f32_e32 v80, v84, v205
	v_exp_f32_e32 v83, v80
	v_sub_f32_e32 v80, v85, v205
	v_add_f32_e32 v10, v11, v9
	v_exp_f32_e32 v84, v80
	v_sub_f32_e32 v80, v86, v205
	v_add_f32_e32 v10, v81, v10
	v_exp_f32_e32 v85, v80
	v_sub_f32_e32 v80, v87, v205
	v_add_f32_e32 v10, v82, v10
	v_exp_f32_e32 v86, v80
	v_sub_f32_e32 v80, v88, v205
	v_add_f32_e32 v10, v83, v10
	v_exp_f32_e32 v87, v80
	v_sub_f32_e32 v80, v89, v205
	v_add_f32_e32 v10, v84, v10
	v_exp_f32_e32 v88, v80
	v_sub_f32_e32 v80, v90, v205
	v_add_f32_e32 v10, v85, v10
	v_exp_f32_e32 v89, v80
	v_sub_f32_e32 v80, v91, v205
	v_add_f32_e32 v10, v86, v10
	v_exp_f32_e32 v90, v80
	v_sub_f32_e32 v80, v92, v205
	v_add_f32_e32 v10, v87, v10
	v_exp_f32_e32 v91, v80
	v_sub_f32_e32 v80, v93, v205
	v_add_f32_e32 v10, v88, v10
	v_exp_f32_e32 v92, v80
	v_sub_f32_e32 v80, v94, v205
	v_add_f32_e32 v10, v89, v10
	v_exp_f32_e32 v93, v80
	v_sub_f32_e32 v80, v95, v205
	v_add_f32_e32 v10, v90, v10
	v_exp_f32_e32 v94, v80
	v_add_f32_e32 v10, v91, v10
	v_add_f32_e32 v10, v92, v10
	v_add_f32_e32 v10, v93, v10
	v_add_f32_e32 v10, v94, v10
	v_add_f32_e32 v208, v8, v10
	v_cvt_pk_bf16_f32 v81, v81, v82
	v_cvt_pk_bf16_f32 v82, v83, v84
	v_cvt_pk_bf16_f32 v8, v87, v88
	v_lshl_add_u32 v84, v204, 1, v219
	v_lshl_add_u32 v88, v203, 1, v219
	v_cvt_pk_bf16_f32 v80, v9, v11
	v_cvt_pk_bf16_f32 v83, v85, v86
	v_cvt_pk_bf16_f32 v9, v89, v90
	v_cvt_pk_bf16_f32 v10, v91, v92
	ds_read_b64 v[238:239], v84 offset:8192
	ds_read_b64 v[242:243], v84 offset:12288
	ds_read_b64 v[240:241], v88 offset:8192
	ds_read_b64 v[244:245], v88 offset:12288
	v_cvt_pk_bf16_f32 v11, v93, v94
	v_cvt_pk_bf16_f32 v14, v14, v15
	v_cvt_pk_bf16_f32 v15, v96, v97
	s_waitcnt lgkmcnt(0)
	v_mfma_f32_32x32x16_bf16 v[64:79], v[238:241], v[12:15], v[64:79]
	v_cvt_pk_bf16_f32 v6, v98, v99
	v_cvt_pk_bf16_f32 v7, v100, v101
	s_add_i32 s45, s45, 1
	s_add_i32 s2, s38, 1
	s_cmp_lg_u32 s38, 2
	s_cselect_b32 s38, s2, 0
	s_mov_b64 s[2:3], 0x1000
	v_mfma_f32_32x32x16_bf16 v[32:47], v[238:241], v[80:83], v[32:47]
	v_lshl_add_u64 v[162:163], v[162:163], 0, s[22:23]
	v_lshl_add_u64 v[164:165], v[164:165], 0, s[2:3]
	v_lshl_add_u64 v[166:167], v[166:167], 0, s[24:25]
	s_cmp_lg_u32 s45, 3
	v_mfma_f32_32x32x16_bf16 v[48:63], v[242:245], v[12:15], v[48:63]
	v_lshl_add_u32 v12, v202, 1, v219
	ds_read2st64_b64 v[12:15], v12 offset0:16 offset1:24
	s_waitcnt lgkmcnt(0)
	v_mov_b32_e32 v84, v12
	v_mfma_f32_32x32x16_bf16 v[16:31], v[242:245], v[80:83], v[16:31]
	v_lshl_add_u32 v80, v201, 1, v219
	ds_read2st64_b64 v[80:83], v80 offset0:16 offset1:24
	v_mov_b32_e32 v85, v13
	s_waitcnt lgkmcnt(0)
	v_mov_b32_e32 v86, v80
	v_mov_b32_e32 v87, v81
	v_mov_b32_e32 v80, v14
	v_mov_b32_e32 v81, v15
	v_mfma_f32_32x32x16_bf16 v[64:79], v[84:87], v[4:7], v[64:79]
	v_mfma_f32_32x32x16_bf16 v[32:47], v[84:87], v[8:11], v[32:47]
	v_mfma_f32_32x32x16_bf16 v[48:63], v[80:83], v[4:7], v[48:63]
	v_mfma_f32_32x32x16_bf16 v[16:31], v[80:83], v[8:11], v[16:31]
	s_cbranch_scc0 .LBB0_214

.LBB0_210:
	v_sub_f32_e32 v4, v96, v1
	v_exp_f32_e32 v4, v4
	v_sub_f32_e32 v6, v97, v1
	v_exp_f32_e32 v6, v6
	v_sub_f32_e32 v7, v98, v1
	v_exp_f32_e32 v7, v7
	v_sub_f32_e32 v8, v99, v1
	v_exp_f32_e32 v8, v8
	v_add_f32_e32 v5, v6, v4
	v_add_f32_e32 v5, v7, v5
	v_add_f32_e32 v5, v8, v5
	v_cvt_pk_bf16_f32 v97, v7, v8
	v_sub_f32_e32 v8, v80, v205
	v_exp_f32_e32 v224, v8
	v_sub_f32_e32 v8, v81, v205
	v_exp_f32_e32 v226, v8
	v_sub_f32_e32 v8, v82, v205
	v_exp_f32_e32 v227, v8
	v_sub_f32_e32 v8, v83, v205
	v_exp_f32_e32 v228, v8
	v_sub_f32_e32 v8, v84, v205
	v_exp_f32_e32 v229, v8
	v_sub_f32_e32 v8, v85, v205
	v_exp_f32_e32 v230, v8
	v_sub_f32_e32 v8, v86, v205
	v_exp_f32_e32 v231, v8
	v_sub_f32_e32 v8, v87, v205
	v_exp_f32_e32 v232, v8
	v_sub_f32_e32 v8, v88, v205
	v_exp_f32_e32 v233, v8
	v_sub_f32_e32 v8, v89, v205
	v_add3_u32 v219, v219, v209, v160
	v_exp_f32_e32 v234, v8
	v_sub_f32_e32 v8, v90, v205
	v_lshl_add_u32 v84, v211, 1, v219
	v_lshl_add_u32 v88, v210, 1, v219
	v_exp_f32_e32 v235, v8
	v_sub_f32_e32 v8, v91, v205
	ds_read_b64 v[238:239], v84 offset:8192
	ds_read_b64 v[242:243], v84 offset:12288
	ds_read_b64 v[240:241], v88 offset:8192
	ds_read_b64 v[244:245], v88 offset:12288
	v_exp_f32_e32 v236, v8
	v_sub_f32_e32 v8, v92, v205
	v_sub_f32_e32 v9, v100, v1
	v_sub_f32_e32 v96, v103, v1
	v_exp_f32_e32 v237, v8
	v_sub_f32_e32 v8, v93, v205
	v_exp_f32_e32 v9, v9
	v_sub_f32_e32 v10, v101, v1
	v_exp_f32_e32 v99, v96
	v_sub_f32_e32 v96, v104, v1
	v_exp_f32_e32 v222, v8
	v_sub_f32_e32 v8, v94, v205
	v_exp_f32_e32 v10, v10
	v_sub_f32_e32 v11, v102, v1
	v_exp_f32_e32 v100, v96
	v_sub_f32_e32 v96, v105, v1
	v_exp_f32_e32 v223, v8
	v_sub_f32_e32 v8, v95, v205
	s_waitcnt lgkmcnt(0)
	v_exp_f32_e32 v11, v11
	v_exp_f32_e32 v101, v96
	v_sub_f32_e32 v96, v106, v1
	v_exp_f32_e32 v102, v96
	v_sub_f32_e32 v96, v107, v1
	v_add_f32_e32 v5, v9, v5
	v_exp_f32_e32 v103, v96
	v_sub_f32_e32 v96, v108, v1
	v_add_f32_e32 v5, v10, v5
	v_exp_f32_e32 v104, v96
	v_sub_f32_e32 v96, v109, v1
	v_cvt_pk_bf16_f32 v80, v224, v226
	v_cvt_pk_bf16_f32 v81, v227, v228
	v_cvt_pk_bf16_f32 v82, v229, v230
	v_cvt_pk_bf16_f32 v83, v231, v232
	v_add_f32_e32 v5, v11, v5
	v_exp_f32_e32 v105, v96
	v_sub_f32_e32 v96, v110, v1
	v_mfma_f32_32x32x16_bf16 v[32:47], v[238:241], v[80:83], v[32:47]
	v_lshl_add_u32 v84, v206, 1, v219
	v_add_f32_e32 v5, v99, v5
	v_exp_f32_e32 v106, v96
	v_sub_f32_e32 v96, v111, v1
	ds_read2st64_b64 v[84:87], v84 offset0:16 offset1:24
	v_add_f32_e32 v5, v100, v5
	v_exp_f32_e32 v107, v96
	v_mfma_f32_32x32x16_bf16 v[16:31], v[242:245], v[80:83], v[16:31]
	v_lshl_add_u32 v80, v207, 1, v219
	ds_read2st64_b64 v[80:83], v80 offset0:16 offset1:24
	v_cvt_pk_bf16_f32 v96, v4, v6
	v_cvt_pk_bf16_f32 v98, v9, v10
	v_cvt_pk_bf16_f32 v99, v11, v99
	v_add_f32_e32 v5, v101, v5
	v_add_f32_e32 v5, v102, v5
	v_mfma_f32_32x32x16_bf16 v[64:79], v[238:241], v[96:99], v[64:79]
	v_add_f32_e32 v5, v103, v5
	v_add_f32_e32 v5, v104, v5
	v_add_f32_e32 v5, v105, v5
	v_add_f32_e32 v5, v106, v5
	v_add_f32_e32 v5, v107, v5
	v_add_f32_e32 v3, v3, v5
	v_cvt_pk_bf16_f32 v4, v100, v101
	v_mfma_f32_32x32x16_bf16 v[48:63], v[242:245], v[96:99], v[48:63]
	s_waitcnt lgkmcnt(0)
	v_mov_b32_e32 v88, v80
	v_mov_b32_e32 v89, v81
	v_mov_b32_e32 v90, v84
	v_mov_b32_e32 v91, v85
	v_mov_b32_e32 v84, v82
	v_mov_b32_e32 v85, v83
	v_cvt_pk_bf16_f32 v5, v102, v103
	v_cvt_pk_bf16_f32 v6, v104, v105
	v_cvt_pk_bf16_f32 v7, v106, v107
	v_exp_f32_e32 v225, v8
	v_cvt_pk_bf16_f32 v8, v233, v234
	v_mfma_f32_32x32x16_bf16 v[64:79], v[88:91], v[4:7], v[64:79]
	v_cvt_pk_bf16_f32 v9, v235, v236
	v_cvt_pk_bf16_f32 v10, v237, v222
	v_cvt_pk_bf16_f32 v11, v223, v225
	v_mfma_f32_32x32x16_bf16 v[48:63], v[84:87], v[4:7], v[48:63]
	ds_read_b128 v[4:7], v220 offset:4096
	v_mfma_f32_32x32x16_bf16 v[32:47], v[88:91], v[8:11], v[32:47]
	v_mfma_f32_32x32x16_bf16 v[16:31], v[84:87], v[8:11], v[16:31]
	s_waitcnt lgkmcnt(0)
	v_mfma_f32_32x32x16_bf16 v[96:111], v[4:7], v[152:155], 0
	v_mfma_f32_32x32x16_bf16 v[80:95], v[4:7], v[156:159], 0
	ds_read_b128 v[4:7], v14 offset:4096
	s_waitcnt lgkmcnt(0)
	v_mfma_f32_32x32x16_bf16 v[96:111], v[4:7], v[140:143], v[96:111]
	v_mfma_f32_32x32x16_bf16 v[80:95], v[4:7], v[148:151], v[80:95]
	ds_read_b128 v[4:7], v221 offset:4096
	s_waitcnt lgkmcnt(0)
	v_mfma_f32_32x32x16_bf16 v[96:111], v[4:7], v[136:139], v[96:111]
	v_mfma_f32_32x32x16_bf16 v[80:95], v[4:7], v[144:147], v[80:95]
	ds_read_b128 v[4:7], v13 offset:4096
	s_waitcnt lgkmcnt(0)
	v_mfma_f32_32x32x16_bf16 v[96:111], v[4:7], v[124:127], v[96:111]
	v_mfma_f32_32x32x16_bf16 v[80:95], v[4:7], v[132:135], v[80:95]
	ds_read_b128 v[4:7], v15 offset:18432
	s_waitcnt lgkmcnt(0)
	v_mfma_f32_32x32x16_bf16 v[96:111], v[4:7], v[120:123], v[96:111]
	v_mfma_f32_32x32x16_bf16 v[80:95], v[4:7], v[128:131], v[80:95]
	ds_read_b128 v[4:7], v12 offset:18432
	s_waitcnt lgkmcnt(0)
	v_mfma_f32_32x32x16_bf16 v[96:111], v[4:7], v[112:115], v[96:111]
	v_mfma_f32_32x32x16_bf16 v[80:95], v[4:7], v[116:119], v[80:95]
	s_nop 10
	v_max_f32_e32 v4, v97, v97
	v_max_f32_e32 v5, v96, v96
	v_max_f32_e32 v4, v5, v4
	v_max3_f32 v4, v4, v98, v99
	v_max3_f32 v4, v4, v100, v101
	v_max3_f32 v4, v4, v102, v103
	v_max3_f32 v4, v4, v104, v105
	v_max3_f32 v4, v4, v106, v107
	v_max3_f32 v4, v4, v108, v109
	v_max3_f32 v4, v4, v110, v111
	v_mov_b32_e32 v5, v4
	s_nop 1
	v_permlane32_swap_b32_e32 v5, v4
	s_nop 1
	s_waitcnt lgkmcnt(0)
	v_max_f32_e32 v5, v5, v5
	v_max_f32_e32 v4, v4, v5
	v_add_f32_e32 v5, 0x41000000, v1
	v_cmp_gt_f32_e32 vcc, v4, v5
	s_cbranch_vccz .LBB0_212
	v_max_f32_e32 v4, v4, v4
	v_max_f32_e32 v5, v1, v1
	v_max_f32_e32 v5, v5, v4
	v_sub_f32_e32 v1, v1, v5
	v_exp_f32_e32 v4, v1
	v_mov_b32_e32 v1, v5
	v_mul_f32_e32 v3, v3, v4
	v_pk_mul_f32 v[78:79], v[78:79], v[4:5] op_sel_hi:[1,0]
	v_pk_mul_f32 v[76:77], v[76:77], v[4:5] op_sel_hi:[1,0]
	v_pk_mul_f32 v[74:75], v[74:75], v[4:5] op_sel_hi:[1,0]
	v_pk_mul_f32 v[72:73], v[72:73], v[4:5] op_sel_hi:[1,0]
	v_pk_mul_f32 v[70:71], v[70:71], v[4:5] op_sel_hi:[1,0]
	v_pk_mul_f32 v[68:69], v[68:69], v[4:5] op_sel_hi:[1,0]
	v_pk_mul_f32 v[66:67], v[66:67], v[4:5] op_sel_hi:[1,0]
	v_pk_mul_f32 v[64:65], v[64:65], v[4:5] op_sel_hi:[1,0]
	v_pk_mul_f32 v[62:63], v[62:63], v[4:5] op_sel_hi:[1,0]
	v_pk_mul_f32 v[60:61], v[60:61], v[4:5] op_sel_hi:[1,0]
	v_pk_mul_f32 v[58:59], v[58:59], v[4:5] op_sel_hi:[1,0]
	v_pk_mul_f32 v[56:57], v[56:57], v[4:5] op_sel_hi:[1,0]
	v_pk_mul_f32 v[54:55], v[54:55], v[4:5] op_sel_hi:[1,0]
	v_pk_mul_f32 v[52:53], v[52:53], v[4:5] op_sel_hi:[1,0]
	v_pk_mul_f32 v[50:51], v[50:51], v[4:5] op_sel_hi:[1,0]
	v_pk_mul_f32 v[48:49], v[48:49], v[4:5] op_sel_hi:[1,0]
.LBB0_212:
	v_add_f32_e32 v4, v226, v224
	v_add_f32_e32 v4, v227, v4
	v_max_f32_e32 v5, v81, v81
	v_max_f32_e32 v6, v80, v80
	v_add_f32_e32 v4, v228, v4
	v_max_f32_e32 v5, v6, v5
	v_add_f32_e32 v4, v229, v4
	v_max3_f32 v5, v5, v82, v83
	v_add_f32_e32 v4, v230, v4
	v_max3_f32 v5, v5, v84, v85
	v_add_f32_e32 v4, v231, v4
	v_max3_f32 v5, v5, v86, v87
	v_add_f32_e32 v4, v232, v4
	v_max3_f32 v5, v5, v88, v89
	v_add_f32_e32 v4, v233, v4
	v_max3_f32 v5, v5, v90, v91
	v_add_f32_e32 v4, v234, v4
	v_max3_f32 v5, v5, v92, v93
	v_add_f32_e32 v4, v235, v4
	v_max3_f32 v5, v5, v94, v95
	v_add_f32_e32 v4, v236, v4
	v_mov_b32_e32 v6, v5
	s_nop 1
	v_permlane32_swap_b32_e32 v6, v5
	s_nop 1
	v_add_f32_e32 v4, v237, v4
	v_add_f32_e32 v4, v222, v4
	v_add_f32_e32 v4, v223, v4
	v_add_f32_e32 v4, v225, v4
	v_add_f32_e32 v8, v208, v4
	s_waitcnt lgkmcnt(0)
	v_max_f32_e32 v4, v6, v6
	v_max_f32_e32 v4, v5, v4
	v_add_f32_e32 v5, 0x41000000, v205
	v_cmp_gt_f32_e32 vcc, v4, v5
	s_cbranch_vccz .LBB0_203
	v_max_f32_e32 v4, v4, v4
	v_max_f32_e32 v5, v205, v205
	v_max_f32_e32 v5, v5, v4
	v_sub_f32_e32 v4, v205, v5
	v_exp_f32_e32 v4, v4
	v_mov_b32_e32 v205, v5
	v_mul_f32_e32 v8, v8, v4
	v_pk_mul_f32 v[46:47], v[46:47], v[4:5] op_sel_hi:[1,0]
	v_pk_mul_f32 v[44:45], v[44:45], v[4:5] op_sel_hi:[1,0]
	v_pk_mul_f32 v[42:43], v[42:43], v[4:5] op_sel_hi:[1,0]
	v_pk_mul_f32 v[40:41], v[40:41], v[4:5] op_sel_hi:[1,0]
	v_pk_mul_f32 v[38:39], v[38:39], v[4:5] op_sel_hi:[1,0]
	v_pk_mul_f32 v[36:37], v[36:37], v[4:5] op_sel_hi:[1,0]
	v_pk_mul_f32 v[34:35], v[34:35], v[4:5] op_sel_hi:[1,0]
	v_pk_mul_f32 v[32:33], v[32:33], v[4:5] op_sel_hi:[1,0]
	v_pk_mul_f32 v[30:31], v[30:31], v[4:5] op_sel_hi:[1,0]
	v_pk_mul_f32 v[28:29], v[28:29], v[4:5] op_sel_hi:[1,0]
	v_pk_mul_f32 v[26:27], v[26:27], v[4:5] op_sel_hi:[1,0]
	v_pk_mul_f32 v[24:25], v[24:25], v[4:5] op_sel_hi:[1,0]
	v_pk_mul_f32 v[22:23], v[22:23], v[4:5] op_sel_hi:[1,0]
	v_pk_mul_f32 v[20:21], v[20:21], v[4:5] op_sel_hi:[1,0]
	v_pk_mul_f32 v[18:19], v[18:19], v[4:5] op_sel_hi:[1,0]
	v_pk_mul_f32 v[16:17], v[16:17], v[4:5] op_sel_hi:[1,0]
	s_branch .LBB0_203

.LBB0_218:
	v_sub_f32_e32 v4, v96, v1
	v_exp_f32_e32 v4, v4
	v_sub_f32_e32 v6, v97, v1
	v_exp_f32_e32 v6, v6
	v_sub_f32_e32 v7, v98, v1
	v_exp_f32_e32 v7, v7
	v_sub_f32_e32 v8, v99, v1
	v_exp_f32_e32 v8, v8
	v_sub_f32_e32 v9, v100, v1
	v_exp_f32_e32 v9, v9
	v_sub_f32_e32 v10, v101, v1
	v_add_f32_e32 v5, v6, v4
	v_exp_f32_e32 v10, v10
	v_sub_f32_e32 v11, v102, v1
	v_add_f32_e32 v5, v7, v5
	v_exp_f32_e32 v11, v11
	v_sub_f32_e32 v12, v103, v1
	v_add_f32_e32 v5, v8, v5
	v_exp_f32_e32 v99, v12
	v_sub_f32_e32 v12, v104, v1
	v_add_f32_e32 v5, v9, v5
	v_exp_f32_e32 v100, v12
	v_sub_f32_e32 v12, v105, v1
	v_add_f32_e32 v5, v10, v5
	v_exp_f32_e32 v101, v12
	v_sub_f32_e32 v12, v106, v1
	v_add_f32_e32 v5, v11, v5
	v_exp_f32_e32 v102, v12
	v_sub_f32_e32 v12, v107, v1
	v_add_f32_e32 v5, v99, v5
	v_exp_f32_e32 v103, v12
	v_sub_f32_e32 v12, v108, v1
	v_add_f32_e32 v5, v100, v5
	v_exp_f32_e32 v104, v12
	v_sub_f32_e32 v12, v109, v1
	v_add_f32_e32 v5, v101, v5
	v_exp_f32_e32 v105, v12
	v_sub_f32_e32 v12, v110, v1
	v_add_f32_e32 v5, v102, v5
	v_exp_f32_e32 v106, v12
	v_sub_f32_e32 v12, v111, v1
	v_add_f32_e32 v5, v103, v5
	v_exp_f32_e32 v107, v12
	v_add_f32_e32 v5, v104, v5
	v_add_f32_e32 v5, v105, v5
	v_add_f32_e32 v5, v106, v5
	v_add_f32_e32 v5, v107, v5
	v_add_f32_e32 v12, v3, v5
	v_sub_f32_e32 v3, v80, v205
	v_exp_f32_e32 v167, v3
	v_sub_f32_e32 v3, v81, v205
	v_exp_f32_e32 v213, v3
	v_sub_f32_e32 v3, v82, v205
	v_exp_f32_e32 v214, v3
	v_sub_f32_e32 v3, v83, v205
	v_exp_f32_e32 v216, v3
	v_sub_f32_e32 v3, v84, v205
	v_exp_f32_e32 v217, v3
	v_sub_f32_e32 v3, v85, v205
	v_exp_f32_e32 v218, v3
	v_sub_f32_e32 v3, v86, v205
	v_exp_f32_e32 v219, v3
	v_sub_f32_e32 v3, v87, v205
	v_exp_f32_e32 v220, v3
	v_sub_f32_e32 v3, v88, v205
	v_exp_f32_e32 v221, v3
	v_sub_f32_e32 v3, v89, v205
	v_exp_f32_e32 v222, v3
	v_sub_f32_e32 v3, v90, v205
	v_exp_f32_e32 v223, v3
	v_sub_f32_e32 v3, v91, v205
	v_exp_f32_e32 v224, v3
	v_sub_f32_e32 v3, v92, v205
	v_exp_f32_e32 v225, v3
	v_sub_f32_e32 v3, v93, v205
	v_exp_f32_e32 v165, v3
	v_sub_f32_e32 v3, v94, v205
	v_exp_f32_e32 v166, v3
	v_sub_f32_e32 v3, v95, v205
	v_exp_f32_e32 v212, v3
	v_add3_u32 v3, v215, v209, v160
	v_lshl_add_u32 v84, v211, 1, v3
	v_lshl_add_u32 v88, v210, 1, v3
	ds_read_b64 v[238:239], v84 offset:8192
	ds_read_b64 v[242:243], v84 offset:12288
	ds_read_b64 v[240:241], v88 offset:8192
	ds_read_b64 v[244:245], v88 offset:12288
	v_cvt_pk_bf16_f32 v80, v167, v213
	v_cvt_pk_bf16_f32 v81, v214, v216
	v_cvt_pk_bf16_f32 v82, v217, v218
	s_waitcnt lgkmcnt(0)
	v_cvt_pk_bf16_f32 v83, v219, v220
	v_lshl_add_u32 v84, v206, 1, v3
	ds_read2st64_b64 v[84:87], v84 offset0:16 offset1:24
	v_mfma_f32_32x32x16_bf16 v[32:47], v[238:241], v[80:83], v[32:47]
	v_cvt_pk_bf16_f32 v96, v4, v6
	v_cvt_pk_bf16_f32 v97, v7, v8
	v_cvt_pk_bf16_f32 v98, v9, v10
	v_cvt_pk_bf16_f32 v99, v11, v99
	v_cvt_pk_bf16_f32 v4, v100, v101
	v_cvt_pk_bf16_f32 v5, v102, v103
	v_cvt_pk_bf16_f32 v6, v104, v105
	v_mfma_f32_32x32x16_bf16 v[16:31], v[242:245], v[80:83], v[16:31]
	v_lshl_add_u32 v80, v207, 1, v3
	ds_read2st64_b64 v[80:83], v80 offset0:16 offset1:24
	v_cvt_pk_bf16_f32 v7, v106, v107
	v_cvt_pk_bf16_f32 v8, v221, v222
	v_cvt_pk_bf16_f32 v9, v223, v224
	v_cvt_pk_bf16_f32 v10, v225, v165
	v_cvt_pk_bf16_f32 v11, v166, v212
	v_mfma_f32_32x32x16_bf16 v[64:79], v[238:241], v[96:99], v[64:79]
	v_mfma_f32_32x32x16_bf16 v[48:63], v[242:245], v[96:99], v[48:63]
	s_waitcnt lgkmcnt(0)
	v_mov_b32_e32 v88, v80
	v_mov_b32_e32 v89, v81
	v_mov_b32_e32 v90, v84
	v_mov_b32_e32 v91, v85
	v_mov_b32_e32 v84, v82
	v_mov_b32_e32 v85, v83
	v_mfma_f32_32x32x16_bf16 v[64:79], v[88:91], v[4:7], v[64:79]
	s_nop 0
	v_mfma_f32_32x32x16_bf16 v[48:63], v[84:87], v[4:7], v[48:63]
	ds_read_b128 v[4:7], v14 offset:4096
	v_mfma_f32_32x32x16_bf16 v[32:47], v[88:91], v[8:11], v[32:47]
	v_mfma_f32_32x32x16_bf16 v[16:31], v[84:87], v[8:11], v[16:31]
	s_waitcnt lgkmcnt(0)
	v_mfma_f32_32x32x16_bf16 v[96:111], v[4:7], v[152:155], 0
	v_mfma_f32_32x32x16_bf16 v[80:95], v[4:7], v[156:159], 0
	ds_read_b128 v[4:7], v15 offset:4096
	s_waitcnt lgkmcnt(0)
	v_mfma_f32_32x32x16_bf16 v[96:111], v[4:7], v[140:143], v[96:111]
	v_mfma_f32_32x32x16_bf16 v[80:95], v[4:7], v[148:151], v[80:95]
	ds_read_b128 v[4:7], v162 offset:4096
	s_waitcnt lgkmcnt(0)
	v_mfma_f32_32x32x16_bf16 v[96:111], v[4:7], v[136:139], v[96:111]
	v_mfma_f32_32x32x16_bf16 v[80:95], v[4:7], v[144:147], v[80:95]
	ds_read_b128 v[4:7], v163 offset:4096
	s_waitcnt lgkmcnt(0)
	v_mfma_f32_32x32x16_bf16 v[96:111], v[4:7], v[124:127], v[96:111]
	v_mfma_f32_32x32x16_bf16 v[80:95], v[4:7], v[132:135], v[80:95]
	ds_read_b128 v[4:7], v164 offset:18432
	s_waitcnt lgkmcnt(0)
	v_mfma_f32_32x32x16_bf16 v[96:111], v[4:7], v[120:123], v[96:111]
	v_mfma_f32_32x32x16_bf16 v[80:95], v[4:7], v[128:131], v[80:95]
	ds_read_b128 v[4:7], v13 offset:18432
	s_waitcnt lgkmcnt(0)
	v_mfma_f32_32x32x16_bf16 v[96:111], v[4:7], v[112:115], v[96:111]
	v_mfma_f32_32x32x16_bf16 v[80:95], v[4:7], v[116:119], v[80:95]
	s_nop 10
	v_max_f32_e32 v4, v97, v97
	v_max_f32_e32 v5, v96, v96
	v_max_f32_e32 v4, v5, v4
	v_max3_f32 v4, v4, v98, v99
	v_max3_f32 v4, v4, v100, v101
	v_max3_f32 v4, v4, v102, v103
	v_max3_f32 v4, v4, v104, v105
	v_max3_f32 v4, v4, v106, v107
	v_max3_f32 v4, v4, v108, v109
	v_max3_f32 v4, v4, v110, v111
	v_mov_b32_e32 v5, v4
	s_nop 1
	v_permlane32_swap_b32_e32 v5, v4
	s_nop 1
	s_waitcnt lgkmcnt(0)
	v_max_f32_e32 v5, v5, v5
	v_max_f32_e32 v4, v4, v5
	v_add_f32_e32 v5, 0x41000000, v1
	v_cmp_gt_f32_e32 vcc, v4, v5
	s_cbranch_vccz .LBB0_220
	v_max_f32_e32 v4, v4, v4
	v_max_f32_e32 v5, v1, v1
	v_max_f32_e32 v5, v5, v4
	v_sub_f32_e32 v1, v1, v5
	v_exp_f32_e32 v4, v1
	v_mov_b32_e32 v1, v5
	v_mul_f32_e32 v12, v12, v4
	v_pk_mul_f32 v[78:79], v[78:79], v[4:5] op_sel_hi:[1,0]
	v_pk_mul_f32 v[76:77], v[76:77], v[4:5] op_sel_hi:[1,0]
	v_pk_mul_f32 v[74:75], v[74:75], v[4:5] op_sel_hi:[1,0]
	v_pk_mul_f32 v[72:73], v[72:73], v[4:5] op_sel_hi:[1,0]
	v_pk_mul_f32 v[70:71], v[70:71], v[4:5] op_sel_hi:[1,0]
	v_pk_mul_f32 v[68:69], v[68:69], v[4:5] op_sel_hi:[1,0]
	v_pk_mul_f32 v[66:67], v[66:67], v[4:5] op_sel_hi:[1,0]
	v_pk_mul_f32 v[64:65], v[64:65], v[4:5] op_sel_hi:[1,0]
	v_pk_mul_f32 v[62:63], v[62:63], v[4:5] op_sel_hi:[1,0]
	v_pk_mul_f32 v[60:61], v[60:61], v[4:5] op_sel_hi:[1,0]
	v_pk_mul_f32 v[58:59], v[58:59], v[4:5] op_sel_hi:[1,0]
	v_pk_mul_f32 v[56:57], v[56:57], v[4:5] op_sel_hi:[1,0]
	v_pk_mul_f32 v[54:55], v[54:55], v[4:5] op_sel_hi:[1,0]
	v_pk_mul_f32 v[52:53], v[52:53], v[4:5] op_sel_hi:[1,0]
	v_pk_mul_f32 v[50:51], v[50:51], v[4:5] op_sel_hi:[1,0]
	v_pk_mul_f32 v[48:49], v[48:49], v[4:5] op_sel_hi:[1,0]
.LBB0_220:
	v_add_f32_e32 v4, v213, v167
	v_add_f32_e32 v4, v214, v4
	v_max_f32_e32 v5, v81, v81
	v_max_f32_e32 v6, v80, v80
	v_add_f32_e32 v4, v216, v4
	v_max_f32_e32 v5, v6, v5
	v_add_f32_e32 v4, v217, v4
	v_max3_f32 v5, v5, v82, v83
	v_add_f32_e32 v4, v218, v4
	v_max3_f32 v5, v5, v84, v85
	v_add_f32_e32 v4, v219, v4
	v_max3_f32 v5, v5, v86, v87
	v_add_f32_e32 v4, v220, v4
	v_max3_f32 v5, v5, v88, v89
	v_add_f32_e32 v4, v221, v4
	v_max3_f32 v5, v5, v90, v91
	v_add_f32_e32 v4, v222, v4
	v_max3_f32 v5, v5, v92, v93
	v_add_f32_e32 v4, v223, v4
	v_max3_f32 v5, v5, v94, v95
	v_add_f32_e32 v4, v224, v4
	v_mov_b32_e32 v6, v5
	s_nop 1
	v_permlane32_swap_b32_e32 v6, v5
	s_nop 1
	v_add_f32_e32 v4, v225, v4
	v_add_f32_e32 v4, v165, v4
	v_add_f32_e32 v4, v166, v4
	v_add_f32_e32 v4, v212, v4
	v_add_f32_e32 v8, v208, v4
	s_waitcnt lgkmcnt(0)
	v_max_f32_e32 v4, v6, v6
	v_max_f32_e32 v4, v5, v4
	v_add_f32_e32 v5, 0x41000000, v205
	v_cmp_gt_f32_e32 vcc, v4, v5
	s_cbranch_vccz .LBB0_222
	v_max_f32_e32 v4, v4, v4
	v_max_f32_e32 v5, v205, v205
	v_max_f32_e32 v5, v5, v4
	v_sub_f32_e32 v4, v205, v5
	v_exp_f32_e32 v4, v4
	v_mov_b32_e32 v205, v5
	v_mul_f32_e32 v8, v8, v4
	v_pk_mul_f32 v[46:47], v[46:47], v[4:5] op_sel_hi:[1,0]
	v_pk_mul_f32 v[44:45], v[44:45], v[4:5] op_sel_hi:[1,0]
	v_pk_mul_f32 v[42:43], v[42:43], v[4:5] op_sel_hi:[1,0]
	v_pk_mul_f32 v[40:41], v[40:41], v[4:5] op_sel_hi:[1,0]
	v_pk_mul_f32 v[38:39], v[38:39], v[4:5] op_sel_hi:[1,0]
	v_pk_mul_f32 v[36:37], v[36:37], v[4:5] op_sel_hi:[1,0]
	v_pk_mul_f32 v[34:35], v[34:35], v[4:5] op_sel_hi:[1,0]
	v_pk_mul_f32 v[32:33], v[32:33], v[4:5] op_sel_hi:[1,0]
	v_pk_mul_f32 v[30:31], v[30:31], v[4:5] op_sel_hi:[1,0]
	v_pk_mul_f32 v[28:29], v[28:29], v[4:5] op_sel_hi:[1,0]
	v_pk_mul_f32 v[26:27], v[26:27], v[4:5] op_sel_hi:[1,0]
	v_pk_mul_f32 v[24:25], v[24:25], v[4:5] op_sel_hi:[1,0]
	v_pk_mul_f32 v[22:23], v[22:23], v[4:5] op_sel_hi:[1,0]
	v_pk_mul_f32 v[20:21], v[20:21], v[4:5] op_sel_hi:[1,0]
	v_pk_mul_f32 v[18:19], v[18:19], v[4:5] op_sel_hi:[1,0]
	v_pk_mul_f32 v[16:17], v[16:17], v[4:5] op_sel_hi:[1,0]
.LBB0_222:
	v_sub_f32_e32 v4, v96, v1
	v_exp_f32_e32 v9, v4
	v_sub_f32_e32 v5, v97, v1
	v_exp_f32_e32 v10, v5
	v_sub_f32_e32 v5, v98, v1
	v_exp_f32_e32 v11, v5
	v_sub_f32_e32 v5, v99, v1
	v_exp_f32_e32 v13, v5
	v_sub_f32_e32 v5, v100, v1
	v_exp_f32_e32 v14, v5
	v_sub_f32_e32 v5, v101, v1
	v_add_f32_e32 v4, v10, v9
	v_exp_f32_e32 v15, v5
	v_sub_f32_e32 v5, v102, v1
	v_add_f32_e32 v4, v11, v4
	v_exp_f32_e32 v96, v5
	v_sub_f32_e32 v5, v103, v1
	v_add_f32_e32 v4, v13, v4
	v_exp_f32_e32 v97, v5
	v_sub_f32_e32 v5, v104, v1
	v_add_f32_e32 v4, v14, v4
	v_exp_f32_e32 v5, v5
	v_sub_f32_e32 v6, v105, v1
	v_add_f32_e32 v4, v15, v4
	v_exp_f32_e32 v6, v6
	v_sub_f32_e32 v7, v106, v1
	v_add_f32_e32 v4, v96, v4
	v_exp_f32_e32 v7, v7
	v_sub_f32_e32 v98, v107, v1
	v_add_f32_e32 v4, v97, v4
	v_exp_f32_e32 v98, v98
	v_sub_f32_e32 v99, v108, v1
	v_add_f32_e32 v4, v5, v4
	v_exp_f32_e32 v99, v99
	v_sub_f32_e32 v100, v109, v1
	v_add_f32_e32 v4, v6, v4
	v_exp_f32_e32 v100, v100
	v_sub_f32_e32 v101, v110, v1
	v_add_f32_e32 v4, v7, v4
	v_exp_f32_e32 v101, v101
	v_sub_f32_e32 v1, v111, v1
	v_add_f32_e32 v4, v98, v4
	v_exp_f32_e32 v1, v1
	v_add_f32_e32 v4, v99, v4
	v_add_f32_e32 v4, v100, v4
	v_add_f32_e32 v4, v101, v4
	v_add_f32_e32 v4, v1, v4
	v_add_f32_e32 v102, v12, v4
	v_cvt_pk_bf16_f32 v4, v5, v6
	v_cvt_pk_bf16_f32 v5, v7, v98
	v_cvt_pk_bf16_f32 v7, v101, v1
	v_sub_f32_e32 v1, v80, v205
	v_cvt_pk_bf16_f32 v12, v9, v10
	v_exp_f32_e32 v1, v1
	v_sub_f32_e32 v10, v81, v205
	v_cvt_pk_bf16_f32 v13, v11, v13
	v_exp_f32_e32 v10, v10
	v_sub_f32_e32 v11, v82, v205
	v_exp_f32_e32 v11, v11
	v_sub_f32_e32 v80, v83, v205
	v_exp_f32_e32 v81, v80
	v_sub_f32_e32 v80, v84, v205
	v_exp_f32_e32 v82, v80
	v_sub_f32_e32 v80, v85, v205
	v_add_f32_e32 v9, v10, v1
	v_exp_f32_e32 v83, v80
	v_sub_f32_e32 v80, v86, v205
	v_add_f32_e32 v9, v11, v9
	v_exp_f32_e32 v84, v80
	v_sub_f32_e32 v80, v87, v205
	v_add_f32_e32 v9, v81, v9
	v_exp_f32_e32 v85, v80
	v_sub_f32_e32 v80, v88, v205
	v_add_f32_e32 v9, v82, v9
	v_exp_f32_e32 v86, v80
	v_sub_f32_e32 v80, v89, v205
	v_add_f32_e32 v9, v83, v9
	v_exp_f32_e32 v87, v80
	v_sub_f32_e32 v80, v90, v205
	v_add_f32_e32 v9, v84, v9
	v_exp_f32_e32 v88, v80
	v_sub_f32_e32 v80, v91, v205
	v_add_f32_e32 v9, v85, v9
	v_exp_f32_e32 v89, v80
	v_sub_f32_e32 v80, v92, v205
	v_add_f32_e32 v9, v86, v9
	v_exp_f32_e32 v90, v80
	v_sub_f32_e32 v80, v93, v205
	v_add_f32_e32 v9, v87, v9
	v_exp_f32_e32 v91, v80
	v_sub_f32_e32 v80, v94, v205
	v_add_f32_e32 v9, v88, v9
	v_exp_f32_e32 v92, v80
	v_sub_f32_e32 v80, v95, v205
	v_add_f32_e32 v9, v89, v9
	v_exp_f32_e32 v93, v80
	v_add_f32_e32 v9, v90, v9
	v_add_f32_e32 v9, v91, v9
	v_add_f32_e32 v9, v92, v9
	v_add_f32_e32 v9, v93, v9
	v_cvt_pk_bf16_f32 v80, v1, v10
	v_lshl_add_u32 v1, v204, 1, v3
	v_cvt_pk_bf16_f32 v14, v14, v15
	v_cvt_pk_bf16_f32 v15, v96, v97
	v_add_f32_e32 v96, v8, v9
	v_cvt_pk_bf16_f32 v82, v82, v83
	v_cvt_pk_bf16_f32 v83, v84, v85
	v_cvt_pk_bf16_f32 v8, v86, v87
	ds_read2st64_b64 v[84:87], v1 offset0:16 offset1:24
	v_lshl_add_u32 v1, v203, 1, v3
	v_cvt_pk_bf16_f32 v9, v88, v89
	v_cvt_pk_bf16_f32 v10, v90, v91
	ds_read2st64_b64 v[88:91], v1 offset0:16 offset1:24
	v_cvt_pk_bf16_f32 v81, v11, v81
	v_cvt_pk_bf16_f32 v11, v92, v93
	s_waitcnt lgkmcnt(0)
	v_mov_b32_e32 v92, v84
	v_mov_b32_e32 v93, v85
	v_mov_b32_e32 v94, v88
	v_mov_b32_e32 v95, v89
	v_mov_b32_e32 v88, v86
	v_mov_b32_e32 v89, v87
	v_lshl_add_u32 v1, v202, 1, v3
	v_mfma_f32_32x32x16_bf16 v[64:79], v[92:95], v[12:15], v[64:79]
	v_cvt_pk_bf16_f32 v6, v99, v100
	s_lshl_b64 s[2:3], s[36:37], 10
	v_readlane_b32 s0, v252, 53
	s_add_u32 s36, s0, s2
	v_readlane_b32 s0, v252, 54
	s_addc_u32 s37, s0, s3
	s_lshl_b32 s2, s44, 1
	v_mfma_f32_32x32x16_bf16 v[48:63], v[88:91], v[12:15], v[48:63]
	ds_read2st64_b64 v[12:15], v1 offset0:16 offset1:24
	v_lshl_add_u32 v1, v201, 1, v3
	s_add_u32 s2, s36, s2
	s_addc_u32 s3, s37, 0
	s_mov_b32 s0, 0x8000
	s_waitcnt lgkmcnt(0)
	v_mov_b32_e32 v84, v12
	v_mov_b32_e32 v85, v13
	v_mfma_f32_32x32x16_bf16 v[32:47], v[92:95], v[80:83], v[32:47]
	s_mov_b64 s[36:37], 0
	v_mfma_f32_32x32x16_bf16 v[16:31], v[88:91], v[80:83], v[16:31]
	ds_read2st64_b64 v[80:83], v1 offset0:16 offset1:24
	ds_bpermute_b32 v1, v0, v102
	ds_bpermute_b32 v0, v0, v96
	s_waitcnt lgkmcnt(0)
	v_mov_b32_e32 v86, v80
	v_mov_b32_e32 v87, v81
	v_mov_b32_e32 v80, v14
	v_mov_b32_e32 v81, v15
	v_mfma_f32_32x32x16_bf16 v[64:79], v[84:87], v[4:7], v[64:79]
	v_add_f32_e32 v1, v102, v1
	v_add_f32_e32 v0, v96, v0
	v_rcp_f32_e32 v0, v0
	v_mfma_f32_32x32x16_bf16 v[32:47], v[84:87], v[8:11], v[32:47]
	v_mfma_f32_32x32x16_bf16 v[16:31], v[80:83], v[8:11], v[16:31]
	v_rcp_f32_e32 v8, v1
	s_nop 5
	v_pk_mul_f32 v[10:11], v[66:67], v[8:9] op_sel_hi:[1,0]
	v_mfma_f32_32x32x16_bf16 v[48:63], v[80:83], v[4:7], v[48:63]
	v_lshlrev_b32_e32 v4, 10, v161
	v_mov_b32_e32 v161, v2
	v_lshl_add_u64 v[6:7], s[2:3], 0, v[160:161]
	v_mov_b32_e32 v5, v2
	v_lshl_add_u64 v[4:5], v[6:7], 0, v[4:5]
	v_pk_mul_f32 v[6:7], v[64:65], v[8:9] op_sel_hi:[1,0]
	s_nop 0
	v_cvt_pk_bf16_f32 v6, v6, v7
	v_cvt_pk_bf16_f32 v7, v10, v11
	global_store_dwordx2 v[4:5], v[6:7], off
	v_pk_mul_f32 v[6:7], v[68:69], v[8:9] op_sel_hi:[1,0]
	v_pk_mul_f32 v[10:11], v[70:71], v[8:9] op_sel_hi:[1,0]
	v_cvt_pk_bf16_f32 v6, v6, v7
	v_cvt_pk_bf16_f32 v7, v10, v11
	global_store_dwordx2 v[4:5], v[6:7], off offset:16
	v_pk_mul_f32 v[6:7], v[72:73], v[8:9] op_sel_hi:[1,0]
	v_pk_mul_f32 v[10:11], v[74:75], v[8:9] op_sel_hi:[1,0]
	v_cvt_pk_bf16_f32 v6, v6, v7
	v_cvt_pk_bf16_f32 v7, v10, v11
	global_store_dwordx2 v[4:5], v[6:7], off offset:32
	v_pk_mul_f32 v[6:7], v[76:77], v[8:9] op_sel_hi:[1,0]
	v_pk_mul_f32 v[10:11], v[78:79], v[8:9] op_sel_hi:[1,0]
	v_cvt_pk_bf16_f32 v6, v6, v7
	v_cvt_pk_bf16_f32 v7, v10, v11
	global_store_dwordx2 v[4:5], v[6:7], off offset:48
	v_pk_mul_f32 v[6:7], v[48:49], v[8:9] op_sel_hi:[1,0]
	v_pk_mul_f32 v[10:11], v[50:51], v[8:9] op_sel_hi:[1,0]
	v_cvt_pk_bf16_f32 v6, v6, v7
	v_cvt_pk_bf16_f32 v7, v10, v11
	global_store_dwordx2 v[4:5], v[6:7], off offset:64
	v_pk_mul_f32 v[6:7], v[52:53], v[8:9] op_sel_hi:[1,0]
	v_pk_mul_f32 v[10:11], v[54:55], v[8:9] op_sel_hi:[1,0]
	v_cvt_pk_bf16_f32 v6, v6, v7
	v_cvt_pk_bf16_f32 v7, v10, v11
	global_store_dwordx2 v[4:5], v[6:7], off offset:80
	v_pk_mul_f32 v[6:7], v[56:57], v[8:9] op_sel_hi:[1,0]
	v_pk_mul_f32 v[10:11], v[58:59], v[8:9] op_sel_hi:[1,0]
	v_cvt_pk_bf16_f32 v6, v6, v7
	v_cvt_pk_bf16_f32 v7, v10, v11
	global_store_dwordx2 v[4:5], v[6:7], off offset:96
	v_pk_mul_f32 v[6:7], v[60:61], v[8:9] op_sel_hi:[1,0]
	v_pk_mul_f32 v[8:9], v[62:63], v[8:9] op_sel_hi:[1,0]
	v_cvt_pk_bf16_f32 v6, v6, v7
	v_cvt_pk_bf16_f32 v7, v8, v9
	global_store_dwordx2 v[4:5], v[6:7], off offset:112
	v_pk_mul_f32 v[6:7], v[32:33], v[0:1] op_sel_hi:[1,0]
	v_pk_mul_f32 v[8:9], v[34:35], v[0:1] op_sel_hi:[1,0]
	v_add_co_u32_e32 v4, vcc, s0, v4
	v_cvt_pk_bf16_f32 v6, v6, v7
	v_cvt_pk_bf16_f32 v7, v8, v9
	v_addc_co_u32_e32 v5, vcc, 0, v5, vcc
	global_store_dwordx2 v[4:5], v[6:7], off
	v_pk_mul_f32 v[6:7], v[36:37], v[0:1] op_sel_hi:[1,0]
	v_pk_mul_f32 v[8:9], v[38:39], v[0:1] op_sel_hi:[1,0]
	v_cvt_pk_bf16_f32 v6, v6, v7
	v_cvt_pk_bf16_f32 v7, v8, v9
	global_store_dwordx2 v[4:5], v[6:7], off offset:16
	v_pk_mul_f32 v[6:7], v[40:41], v[0:1] op_sel_hi:[1,0]
	v_pk_mul_f32 v[8:9], v[42:43], v[0:1] op_sel_hi:[1,0]
	v_cvt_pk_bf16_f32 v6, v6, v7
	v_cvt_pk_bf16_f32 v7, v8, v9
	global_store_dwordx2 v[4:5], v[6:7], off offset:32
	v_pk_mul_f32 v[6:7], v[44:45], v[0:1] op_sel_hi:[1,0]
	v_pk_mul_f32 v[8:9], v[46:47], v[0:1] op_sel_hi:[1,0]
	v_cvt_pk_bf16_f32 v6, v6, v7
	v_cvt_pk_bf16_f32 v7, v8, v9
	global_store_dwordx2 v[4:5], v[6:7], off offset:48
	v_pk_mul_f32 v[6:7], v[16:17], v[0:1] op_sel_hi:[1,0]
	v_pk_mul_f32 v[8:9], v[18:19], v[0:1] op_sel_hi:[1,0]
	v_cvt_pk_bf16_f32 v6, v6, v7
	v_cvt_pk_bf16_f32 v7, v8, v9
	global_store_dwordx2 v[4:5], v[6:7], off offset:64
	v_pk_mul_f32 v[6:7], v[20:21], v[0:1] op_sel_hi:[1,0]
	v_pk_mul_f32 v[8:9], v[22:23], v[0:1] op_sel_hi:[1,0]
	v_cvt_pk_bf16_f32 v6, v6, v7
	v_cvt_pk_bf16_f32 v7, v8, v9
	global_store_dwordx2 v[4:5], v[6:7], off offset:80
	v_pk_mul_f32 v[6:7], v[24:25], v[0:1] op_sel_hi:[1,0]
	v_pk_mul_f32 v[8:9], v[26:27], v[0:1] op_sel_hi:[1,0]
	v_cvt_pk_bf16_f32 v6, v6, v7
	v_cvt_pk_bf16_f32 v7, v8, v9
	global_store_dwordx2 v[4:5], v[6:7], off offset:96
	v_pk_mul_f32 v[6:7], v[28:29], v[0:1] op_sel_hi:[1,0]
	v_pk_mul_f32 v[0:1], v[30:31], v[0:1] op_sel_hi:[1,0]
	v_cvt_pk_bf16_f32 v6, v6, v7
	v_cvt_pk_bf16_f32 v7, v0, v1
	global_store_dwordx2 v[4:5], v[6:7], off offset:112
	s_waitcnt lgkmcnt(0)
	s_waitcnt vmcnt(0)
	s_barrier
